# stack on v17: FoX Q prologue loads batched, NSA accumulate-store loads batched, prep norm loop rewritten
# baseline (speedup 1.0000x reference)
.LBB0_51:
	s_or_b64 exec, exec, s[4:5]
	s_waitcnt lgkmcnt(0)
	s_barrier
	ds_read_b32 v0, v201
	s_movk_i32 s4, 0x200
	s_waitcnt lgkmcnt(0)
	v_cmp_gt_i32_e32 vcc, s4, v0
	v_readfirstlane_b32 s16, v0
	s_mov_b64 s[4:5], -1
	s_cbranch_vccz .LBB0_46
	s_bfe_u32 s17, s16, 0x30002
	s_and_b32 s19, s16, 3
	s_ashr_i32 s11, s16, 5
	s_lshl_b32 s4, s19, 14
	s_lshl_b32 s5, s17, 16
	s_sub_i32 s14, 15, s11
	s_or_b32 s4, s5, s4
	v_readlane_b32 s5, v253, 34
	s_add_u32 s4, s5, s4
	v_readlane_b32 s5, v253, 35
	v_mov_b32 v137, v198
	s_addc_u32 s5, s5, 0
	s_lshl_b32 s10, s14, 8
	v_and_b32_e32 v11, 0xffffffc0, v137
	v_and_b32_e32 v143, 15, v137
	v_add_u32_e32 v0, s10, v11
	v_or_b32_e32 v130, v0, v143
	v_ashrrev_i32_e32 v131, 31, v130
	s_lshl_b32 s84, s17, 12
	v_ashrrev_i32_e32 v1, 31, v0
	v_lshl_add_u64 v[2:3], v[130:131], 2, s[4:5]
	global_load_dword v131, v[2:3], off
	global_load_dword v155, v[2:3], off offset:64
	global_load_dword v168, v[2:3], off offset:128
	global_load_dword v169, v[2:3], off offset:192
	v_lshl_add_u64 v[128:129], v[0:1], 0, s[84:85]
	v_bfe_u32 v2, v137, 3, 3
	v_or_b32_e32 v3, v128, v2
	v_mov_b64_e32 v[8:9], s[92:93]
	v_mad_u64_u32 v[4:5], s[12:13], v3, s63, v[8:9]
	v_mad_i32_i24 v5, v129, s63, v5
	s_lshl_b32 s12, s19, 7
	s_mov_b32 s13, s85
	v_lshlrev_b32_e32 v3, 4, v137
	v_lshl_add_u64 v[4:5], v[4:5], 0, s[12:13]
	v_and_b32_e32 v152, 0x70, v3
	v_lshl_add_u64 v[4:5], v[4:5], 0, v[152:153]
	v_add_co_u32_e32 v4, vcc, s64, v4
	v_xor_b32_e32 v12, v2, v137
	s_nop 0
	v_addc_co_u32_e32 v5, vcc, 0, v5, vcc
	global_load_dwordx4 v[64:67], v[4:5], off offset:512
	v_add_co_u32_e32 v96, vcc, 0xc000, v4
	s_nop 1
	v_addc_co_u32_e32 v97, vcc, 0, v5, vcc
	global_load_dwordx4 v[68:71], v[96:97], off offset:512
	v_add_co_u32_e32 v98, vcc, 0x18000, v4
	s_nop 1
	v_addc_co_u32_e32 v99, vcc, 0, v5, vcc
	global_load_dwordx4 v[72:75], v[98:99], off offset:512
	v_add_co_u32_e32 v100, vcc, 0x24000, v4
	s_nop 1
	v_addc_co_u32_e32 v101, vcc, 0, v5, vcc
	global_load_dwordx4 v[76:79], v[100:101], off offset:512
	v_add_co_u32_e32 v102, vcc, 0x30000, v4
	s_nop 1
	v_addc_co_u32_e32 v103, vcc, 0, v5, vcc
	global_load_dwordx4 v[80:83], v[102:103], off offset:512
	v_add_co_u32_e32 v104, vcc, 0x3c000, v4
	s_nop 1
	v_addc_co_u32_e32 v105, vcc, 0, v5, vcc
	global_load_dwordx4 v[84:87], v[104:105], off offset:512
	v_add_co_u32_e32 v106, vcc, 0x48000, v4
	s_nop 1
	v_addc_co_u32_e32 v107, vcc, 0, v5, vcc
	global_load_dwordx4 v[88:91], v[106:107], off offset:512
	v_add_co_u32_e32 v108, vcc, 0x54000, v4
	s_nop 1
	v_addc_co_u32_e32 v109, vcc, 0, v5, vcc
	global_load_dwordx4 v[92:95], v[108:109], off offset:512
	s_waitcnt vmcnt(0)
	v_lshlrev_b32_e32 v12, 4, v12
	v_or_b32_e32 v3, v2, v11
	v_and_b32_e32 v12, 0x70, v12
	v_lshl_or_b32 v3, v3, 7, v12
	v_ashrrev_i32_e32 v10, 6, v137
	v_mov_b32_e32 v171, 0
	ds_write_b128 v3, v[64:67] offset:32768
	v_or_b32_e32 v3, 8, v2
	v_or_b32_e32 v4, v128, v3
	v_mad_u64_u32 v[4:5], s[20:21], v4, s63, v[8:9]
	v_mad_i32_i24 v5, v129, s63, v5
	v_lshl_add_u64 v[4:5], v[4:5], 0, s[12:13]
	v_lshl_add_u64 v[4:5], v[4:5], 0, v[152:153]
	v_add_co_u32_e32 v4, vcc, s64, v4
	v_or_b32_e32 v3, v3, v11
	s_nop 0
	v_addc_co_u32_e32 v5, vcc, 0, v5, vcc
	v_lshl_or_b32 v3, v3, 7, v12
	ds_write_b128 v3, v[68:71] offset:32768
	v_or_b32_e32 v3, 16, v2
	v_or_b32_e32 v4, v128, v3
	v_mad_u64_u32 v[4:5], s[20:21], v4, s63, v[8:9]
	v_mad_i32_i24 v5, v129, s63, v5
	v_lshl_add_u64 v[4:5], v[4:5], 0, s[12:13]
	v_lshl_add_u64 v[4:5], v[4:5], 0, v[152:153]
	v_add_co_u32_e32 v4, vcc, s64, v4
	v_or_b32_e32 v3, v3, v11
	s_nop 0
	v_addc_co_u32_e32 v5, vcc, 0, v5, vcc
	v_lshl_or_b32 v3, v3, 7, v12
	ds_write_b128 v3, v[72:75] offset:32768
	v_or_b32_e32 v3, 24, v2
	v_or_b32_e32 v4, v128, v3
	v_mad_u64_u32 v[4:5], s[20:21], v4, s63, v[8:9]
	v_mad_i32_i24 v5, v129, s63, v5
	v_lshl_add_u64 v[4:5], v[4:5], 0, s[12:13]
	v_lshl_add_u64 v[4:5], v[4:5], 0, v[152:153]
	v_add_co_u32_e32 v4, vcc, s64, v4
	v_or_b32_e32 v3, v3, v11
	s_nop 0
	v_addc_co_u32_e32 v5, vcc, 0, v5, vcc
	v_lshl_or_b32 v3, v3, 7, v12
	ds_write_b128 v3, v[76:79] offset:32768
	v_or_b32_e32 v3, 32, v2
	v_or_b32_e32 v4, v128, v3
	v_mad_u64_u32 v[4:5], s[20:21], v4, s63, v[8:9]
	v_mad_i32_i24 v5, v129, s63, v5
	v_lshl_add_u64 v[4:5], v[4:5], 0, s[12:13]
	v_lshl_add_u64 v[4:5], v[4:5], 0, v[152:153]
	v_add_co_u32_e32 v4, vcc, s64, v4
	v_or_b32_e32 v3, v3, v11
	s_nop 0
	v_addc_co_u32_e32 v5, vcc, 0, v5, vcc
	v_lshl_or_b32 v3, v3, 7, v12
	ds_write_b128 v3, v[80:83] offset:32768
	v_or_b32_e32 v3, 40, v2
	v_or_b32_e32 v4, v128, v3
	v_mad_u64_u32 v[4:5], s[20:21], v4, s63, v[8:9]
	v_mad_i32_i24 v5, v129, s63, v5
	v_lshl_add_u64 v[4:5], v[4:5], 0, s[12:13]
	v_lshl_add_u64 v[4:5], v[4:5], 0, v[152:153]
	v_add_co_u32_e32 v4, vcc, s64, v4
	v_or_b32_e32 v3, v3, v11
	s_nop 0
	v_addc_co_u32_e32 v5, vcc, 0, v5, vcc
	v_lshl_or_b32 v3, v3, 7, v12
	ds_write_b128 v3, v[84:87] offset:32768
	v_or_b32_e32 v3, 48, v2
	v_or_b32_e32 v4, v128, v3
	v_mad_u64_u32 v[4:5], s[20:21], v4, s63, v[8:9]
	v_mad_i32_i24 v5, v129, s63, v5
	v_lshl_add_u64 v[4:5], v[4:5], 0, s[12:13]
	v_lshl_add_u64 v[4:5], v[4:5], 0, v[152:153]
	v_add_co_u32_e32 v4, vcc, s64, v4
	v_or_b32_e32 v3, v3, v11
	s_nop 0
	v_addc_co_u32_e32 v5, vcc, 0, v5, vcc
	v_lshl_or_b32 v3, v3, 7, v12
	ds_write_b128 v3, v[88:91] offset:32768
	v_or_b32_e32 v3, 56, v2
	v_or_b32_e32 v4, v128, v3
	v_mad_u64_u32 v[4:5], s[20:21], v4, s63, v[8:9]
	v_mad_i32_i24 v5, v129, s63, v5
	v_lshl_add_u64 v[4:5], v[4:5], 0, s[12:13]
	v_lshl_add_u64 v[4:5], v[4:5], 0, v[152:153]
	v_add_co_u32_e32 v4, vcc, s64, v4
	s_lshl_b32 s20, s14, 2
	s_nop 0
	v_addc_co_u32_e32 v5, vcc, 0, v5, vcc
	v_or_b32_e32 v3, v3, v11
	v_add_u32_e32 v170, s20, v10
	v_lshl_or_b32 v3, v3, 7, v12
	v_cmp_lt_i32_e32 vcc, 0, v170
	ds_write_b128 v3, v[92:95] offset:32768
	s_waitcnt lgkmcnt(0)
	s_barrier
	s_and_saveexec_b64 s[12:13], vcc
	s_cbranch_execz .LBB0_56
	v_lshl_add_u64 v[0:1], v[0:1], 2, s[4:5]
	global_load_dword v0, v[0:1], off
	v_mov_b32_e32 v171, 0
	s_mov_b64 s[14:15], 0
	v_mov_b32_e32 v1, v170

.LBB0_70:
	global_load_dwordx4 v[52:55], v[138:139], off offset:64
	global_load_dwordx2 v[104:105], v[136:137], off
	global_load_dwordx2 v[106:107], v[136:137], off offset:32
	global_load_dwordx2 v[108:109], v[136:137], off offset:64
	global_load_dwordx2 v[110:111], v[136:137], off offset:96
	global_load_dwordx2 v[112:113], v[136:137], off offset:128
	global_load_dwordx2 v[114:115], v[136:137], off offset:160
	global_load_dwordx2 v[116:117], v[136:137], off offset:192
	global_load_dwordx2 v[118:119], v[136:137], off offset:224
	global_load_dwordx2 v[120:121], v[136:137], off offset:256
	global_load_dwordx2 v[122:123], v[136:137], off offset:288
	global_load_dwordx2 v[124:125], v[136:137], off offset:320
	global_load_dwordx2 v[126:127], v[136:137], off offset:352
	global_load_dwordx2 v[128:129], v[136:137], off offset:384
	global_load_dwordx2 v[130:131], v[136:137], off offset:416
	global_load_dwordx2 v[132:133], v[136:137], off offset:448
	global_load_dwordx2 v[134:135], v[136:137], off offset:480
	s_waitcnt vmcnt(16)
	v_div_scale_f32 v56, s[4:5], v48, v48, v52
	v_rcp_f32_e32 v57, v56
	s_nop 0
	v_fma_f32 v58, -v56, v57, 1.0
	v_fmac_f32_e32 v57, v58, v57
	v_div_scale_f32 v58, vcc, v52, v48, v52
	v_mul_f32_e32 v59, v58, v57
	v_fma_f32 v60, -v56, v59, v58
	v_fmac_f32_e32 v59, v60, v57
	v_fma_f32 v56, -v56, v59, v58
	v_div_fmas_f32 v56, v56, v57, v59
	v_div_fixup_f32 v56, v56, v48, v52
	v_div_scale_f32 v48, s[4:5], v50, v50, v53
	v_rcp_f32_e32 v52, v48
	s_nop 0
	v_fma_f32 v57, -v48, v52, 1.0
	v_fmac_f32_e32 v52, v57, v52
	v_div_scale_f32 v57, vcc, v53, v50, v53
	v_mul_f32_e32 v58, v57, v52
	v_fma_f32 v59, -v48, v58, v57
	v_fmac_f32_e32 v58, v59, v52
	v_fma_f32 v48, -v48, v58, v57
	v_div_fmas_f32 v48, v48, v52, v58
	v_div_fixup_f32 v50, v48, v50, v53
	v_div_scale_f32 v48, s[4:5], v49, v49, v54
	v_rcp_f32_e32 v52, v48
	s_nop 0
	v_fma_f32 v53, -v48, v52, 1.0
	v_fmac_f32_e32 v52, v53, v52
	v_div_scale_f32 v53, vcc, v54, v49, v54
	v_mul_f32_e32 v57, v53, v52
	v_fma_f32 v58, -v48, v57, v53
	v_fmac_f32_e32 v57, v58, v52
	v_fma_f32 v48, -v48, v57, v53
	v_div_fmas_f32 v48, v48, v52, v57
	v_div_fixup_f32 v49, v48, v49, v54
	v_div_scale_f32 v48, s[4:5], v51, v51, v55
	v_rcp_f32_e32 v52, v48
	s_mov_b64 s[4:5], 0
	v_fma_f32 v53, -v48, v52, 1.0
	v_fmac_f32_e32 v52, v53, v52
	v_div_scale_f32 v53, vcc, v55, v51, v55
	v_mul_f32_e32 v54, v53, v52
	v_fma_f32 v57, -v48, v54, v53
	v_fmac_f32_e32 v54, v57, v52
	v_fma_f32 v48, -v48, v54, v53
	v_div_fmas_f32 v48, v48, v52, v54
	v_div_fixup_f32 v48, v48, v51, v55
	s_waitcnt vmcnt(15)
	v_mov_b32_e32 v52, v104
	v_mov_b32_e32 v53, v105
	v_lshlrev_b32_e32 v51, 16, v52
	v_and_b32_e32 v52, 0xffff0000, v52
	v_lshlrev_b32_e32 v54, 16, v53
	v_and_b32_e32 v53, 0xffff0000, v53
	v_fmac_f32_e32 v52, v101, v56
	v_fmac_f32_e32 v53, v103, v56
	v_fmac_f32_e32 v51, v100, v56
	v_fmac_f32_e32 v54, v102, v56
	v_cvt_pk_bf16_f32 v52, v51, v52
	v_cvt_pk_bf16_f32 v53, v54, v53
	global_store_dwordx2 v[136:137], v[52:53], off
	s_waitcnt vmcnt(15)
	v_mov_b32_e32 v52, v106
	v_mov_b32_e32 v53, v107
	v_lshlrev_b32_e32 v51, 16, v52
	v_and_b32_e32 v52, 0xffff0000, v52
	v_lshlrev_b32_e32 v54, 16, v53
	v_and_b32_e32 v53, 0xffff0000, v53
	v_fmac_f32_e32 v52, v97, v56
	v_fmac_f32_e32 v53, v99, v56
	v_fmac_f32_e32 v51, v96, v56
	v_fmac_f32_e32 v54, v98, v56
	v_cvt_pk_bf16_f32 v52, v51, v52
	v_cvt_pk_bf16_f32 v53, v54, v53
	global_store_dwordx2 v[136:137], v[52:53], off offset:32
	s_waitcnt vmcnt(15)
	v_mov_b32_e32 v52, v108
	v_mov_b32_e32 v53, v109
	v_lshlrev_b32_e32 v51, 16, v52
	v_and_b32_e32 v52, 0xffff0000, v52
	v_lshlrev_b32_e32 v54, 16, v53
	v_and_b32_e32 v53, 0xffff0000, v53
	v_fmac_f32_e32 v52, v93, v56
	v_fmac_f32_e32 v53, v95, v56
	v_fmac_f32_e32 v51, v92, v56
	v_fmac_f32_e32 v54, v94, v56
	v_cvt_pk_bf16_f32 v52, v51, v52
	v_cvt_pk_bf16_f32 v53, v54, v53
	global_store_dwordx2 v[136:137], v[52:53], off offset:64
	s_waitcnt vmcnt(15)
	v_mov_b32_e32 v52, v110
	v_mov_b32_e32 v53, v111
	v_lshlrev_b32_e32 v51, 16, v52
	v_and_b32_e32 v52, 0xffff0000, v52
	v_lshlrev_b32_e32 v54, 16, v53
	v_and_b32_e32 v53, 0xffff0000, v53
	v_fmac_f32_e32 v52, v89, v56
	v_fmac_f32_e32 v53, v91, v56
	v_fmac_f32_e32 v51, v88, v56
	v_fmac_f32_e32 v54, v90, v56
	v_cvt_pk_bf16_f32 v52, v51, v52
	v_cvt_pk_bf16_f32 v53, v54, v53
	global_store_dwordx2 v[136:137], v[52:53], off offset:96
	s_waitcnt vmcnt(15)
	v_mov_b32_e32 v52, v112
	v_mov_b32_e32 v53, v113
	v_lshlrev_b32_e32 v51, 16, v52
	v_fmac_f32_e32 v51, v36, v50
	v_and_b32_e32 v36, 0xffff0000, v52
	v_fmac_f32_e32 v36, v37, v50
	v_lshlrev_b32_e32 v37, 16, v53
	v_fmac_f32_e32 v37, v38, v50
	v_and_b32_e32 v38, 0xffff0000, v53
	v_fmac_f32_e32 v38, v39, v50
	v_cvt_pk_bf16_f32 v36, v51, v36
	v_cvt_pk_bf16_f32 v37, v37, v38
	global_store_dwordx2 v[136:137], v[36:37], off offset:128
	s_waitcnt vmcnt(15)
	v_mov_b32_e32 v36, v114
	v_mov_b32_e32 v37, v115
	v_lshlrev_b32_e32 v38, 16, v36
	v_fmac_f32_e32 v38, v32, v50
	v_and_b32_e32 v32, 0xffff0000, v36
	v_fmac_f32_e32 v32, v33, v50
	v_lshlrev_b32_e32 v33, 16, v37
	v_fmac_f32_e32 v33, v34, v50
	v_and_b32_e32 v34, 0xffff0000, v37
	v_fmac_f32_e32 v34, v35, v50
	v_cvt_pk_bf16_f32 v32, v38, v32
	v_cvt_pk_bf16_f32 v33, v33, v34
	global_store_dwordx2 v[136:137], v[32:33], off offset:160
	s_waitcnt vmcnt(15)
	v_mov_b32_e32 v32, v116
	v_mov_b32_e32 v33, v117
	v_lshlrev_b32_e32 v34, 16, v32
	v_fmac_f32_e32 v34, v28, v50
	v_and_b32_e32 v28, 0xffff0000, v32
	v_fmac_f32_e32 v28, v29, v50
	v_lshlrev_b32_e32 v29, 16, v33
	v_fmac_f32_e32 v29, v30, v50
	v_and_b32_e32 v30, 0xffff0000, v33
	v_fmac_f32_e32 v30, v31, v50
	v_cvt_pk_bf16_f32 v28, v34, v28
	v_cvt_pk_bf16_f32 v29, v29, v30
	global_store_dwordx2 v[136:137], v[28:29], off offset:192
	s_waitcnt vmcnt(15)
	v_mov_b32_e32 v28, v118
	v_mov_b32_e32 v29, v119
	v_lshlrev_b32_e32 v30, 16, v28
	v_fmac_f32_e32 v30, v24, v50
	v_and_b32_e32 v24, 0xffff0000, v28
	v_fmac_f32_e32 v24, v25, v50
	v_lshlrev_b32_e32 v25, 16, v29
	v_fmac_f32_e32 v25, v26, v50
	v_and_b32_e32 v26, 0xffff0000, v29
	v_fmac_f32_e32 v26, v27, v50
	v_cvt_pk_bf16_f32 v24, v30, v24
	v_cvt_pk_bf16_f32 v25, v25, v26
	global_store_dwordx2 v[136:137], v[24:25], off offset:224
	s_waitcnt vmcnt(15)
	v_mov_b32_e32 v24, v120
	v_mov_b32_e32 v25, v121
	v_lshlrev_b32_e32 v26, 16, v24
	v_and_b32_e32 v24, 0xffff0000, v24
	v_lshlrev_b32_e32 v27, 16, v25
	v_and_b32_e32 v25, 0xffff0000, v25
	v_fmac_f32_e32 v24, v45, v49
	v_fmac_f32_e32 v25, v47, v49
	v_fmac_f32_e32 v26, v44, v49
	v_fmac_f32_e32 v27, v46, v49
	v_cvt_pk_bf16_f32 v24, v26, v24
	v_cvt_pk_bf16_f32 v25, v27, v25
	global_store_dwordx2 v[136:137], v[24:25], off offset:256
	s_waitcnt vmcnt(15)
	v_mov_b32_e32 v24, v122
	v_mov_b32_e32 v25, v123
	v_lshlrev_b32_e32 v26, 16, v24
	v_and_b32_e32 v24, 0xffff0000, v24
	v_lshlrev_b32_e32 v27, 16, v25
	v_and_b32_e32 v25, 0xffff0000, v25
	v_fmac_f32_e32 v24, v41, v49
	v_fmac_f32_e32 v25, v43, v49
	v_fmac_f32_e32 v26, v40, v49
	v_fmac_f32_e32 v27, v42, v49
	v_cvt_pk_bf16_f32 v24, v26, v24
	v_cvt_pk_bf16_f32 v25, v27, v25
	global_store_dwordx2 v[136:137], v[24:25], off offset:288
	s_waitcnt vmcnt(15)
	v_mov_b32_e32 v24, v124
	v_mov_b32_e32 v25, v125
	v_lshlrev_b32_e32 v26, 16, v24
	v_fmac_f32_e32 v26, v20, v49
	v_and_b32_e32 v20, 0xffff0000, v24
	v_fmac_f32_e32 v20, v21, v49
	v_lshlrev_b32_e32 v21, 16, v25
	v_fmac_f32_e32 v21, v22, v49
	v_and_b32_e32 v22, 0xffff0000, v25
	v_fmac_f32_e32 v22, v23, v49
	v_cvt_pk_bf16_f32 v20, v26, v20
	v_cvt_pk_bf16_f32 v21, v21, v22
	global_store_dwordx2 v[136:137], v[20:21], off offset:320
	s_waitcnt vmcnt(15)
	v_mov_b32_e32 v20, v126
	v_mov_b32_e32 v21, v127
	v_lshlrev_b32_e32 v22, 16, v20
	v_fmac_f32_e32 v22, v16, v49
	v_and_b32_e32 v16, 0xffff0000, v20
	v_fmac_f32_e32 v16, v17, v49
	v_lshlrev_b32_e32 v17, 16, v21
	v_fmac_f32_e32 v17, v18, v49
	v_and_b32_e32 v18, 0xffff0000, v21
	v_fmac_f32_e32 v18, v19, v49
	v_cvt_pk_bf16_f32 v16, v22, v16
	v_cvt_pk_bf16_f32 v17, v17, v18
	global_store_dwordx2 v[136:137], v[16:17], off offset:352
	s_waitcnt vmcnt(15)
	v_mov_b32_e32 v16, v128
	v_mov_b32_e32 v17, v129
	v_lshlrev_b32_e32 v18, 16, v16
	v_fmac_f32_e32 v18, v12, v48
	v_and_b32_e32 v12, 0xffff0000, v16
	v_fmac_f32_e32 v12, v13, v48
	v_lshlrev_b32_e32 v13, 16, v17
	v_fmac_f32_e32 v13, v14, v48
	v_and_b32_e32 v14, 0xffff0000, v17
	v_fmac_f32_e32 v14, v15, v48
	v_cvt_pk_bf16_f32 v12, v18, v12
	v_cvt_pk_bf16_f32 v13, v13, v14
	global_store_dwordx2 v[136:137], v[12:13], off offset:384
	s_waitcnt vmcnt(15)
	v_mov_b32_e32 v12, v130
	v_mov_b32_e32 v13, v131
	v_lshlrev_b32_e32 v14, 16, v12
	v_fmac_f32_e32 v14, v8, v48
	v_and_b32_e32 v8, 0xffff0000, v12
	v_fmac_f32_e32 v8, v9, v48
	v_lshlrev_b32_e32 v9, 16, v13
	v_fmac_f32_e32 v9, v10, v48
	v_and_b32_e32 v10, 0xffff0000, v13
	v_fmac_f32_e32 v10, v11, v48
	v_cvt_pk_bf16_f32 v8, v14, v8
	v_cvt_pk_bf16_f32 v9, v9, v10
	global_store_dwordx2 v[136:137], v[8:9], off offset:416
	s_waitcnt vmcnt(15)
	v_mov_b32_e32 v8, v132
	v_mov_b32_e32 v9, v133
	v_lshlrev_b32_e32 v10, 16, v8
	v_fmac_f32_e32 v10, v4, v48
	v_and_b32_e32 v4, 0xffff0000, v8
	v_fmac_f32_e32 v4, v5, v48
	v_lshlrev_b32_e32 v5, 16, v9
	v_fmac_f32_e32 v5, v6, v48
	v_and_b32_e32 v6, 0xffff0000, v9
	v_fmac_f32_e32 v6, v7, v48
	v_cvt_pk_bf16_f32 v4, v10, v4
	v_cvt_pk_bf16_f32 v5, v5, v6
	global_store_dwordx2 v[136:137], v[4:5], off offset:448
	s_waitcnt vmcnt(15)
	v_mov_b32_e32 v4, v134
	v_mov_b32_e32 v5, v135
	v_lshlrev_b32_e32 v6, 16, v4
	v_fmac_f32_e32 v6, v0, v48
	v_and_b32_e32 v0, 0xffff0000, v4
	v_fmac_f32_e32 v0, v1, v48
	v_lshlrev_b32_e32 v1, 16, v5
	v_fmac_f32_e32 v1, v2, v48
	v_and_b32_e32 v2, 0xffff0000, v5
	v_fmac_f32_e32 v2, v3, v48
	v_cvt_pk_bf16_f32 v0, v6, v0
	v_cvt_pk_bf16_f32 v1, v1, v2
	global_store_dwordx2 v[136:137], v[0:1], off offset:480
	s_barrier

.LBB0_109:
	global_load_dwordx4 v[68:71], v[138:139], off offset:32
	global_load_dwordx2 v[222:223], v[136:137], off offset:32
	global_load_dwordx2 v[224:225], v[136:137], off offset:64
	global_load_dwordx2 v[226:227], v[136:137], off offset:96
	global_load_dwordx2 v[228:229], v[136:137], off offset:128
	global_load_dwordx2 v[230:231], v[136:137], off offset:160
	global_load_dwordx2 v[232:233], v[136:137], off offset:192
	global_load_dwordx2 v[234:235], v[136:137], off offset:224
	global_load_dwordx2 v[236:237], v[136:137], off offset:256
	global_load_dwordx2 v[238:239], v[136:137], off offset:288
	global_load_dwordx2 v[240:241], v[136:137], off offset:320
	global_load_dwordx2 v[242:243], v[136:137], off offset:352
	global_load_dwordx2 v[244:245], v[136:137], off offset:384
	global_load_dwordx2 v[246:247], v[136:137], off offset:416
	global_load_dwordx2 v[248:249], v[136:137], off offset:448
	global_load_dwordx2 v[250:251], v[136:137], off offset:480
	s_waitcnt vmcnt(15)
	v_div_scale_f32 v72, s[4:5], v64, v64, v68
	v_rcp_f32_e32 v73, v72
	s_nop 0
	v_fma_f32 v74, -v72, v73, 1.0
	v_fmac_f32_e32 v73, v74, v73
	v_div_scale_f32 v74, vcc, v68, v64, v68
	v_mul_f32_e32 v75, v74, v73
	v_fma_f32 v76, -v72, v75, v74
	v_fmac_f32_e32 v75, v76, v73
	v_fma_f32 v72, -v72, v75, v74
	v_div_fmas_f32 v72, v72, v73, v75
	v_div_fixup_f32 v72, v72, v64, v68
	v_div_scale_f32 v64, s[4:5], v66, v66, v69
	v_rcp_f32_e32 v68, v64
	s_nop 0
	v_fma_f32 v73, -v64, v68, 1.0
	v_fmac_f32_e32 v68, v73, v68
	v_div_scale_f32 v73, vcc, v69, v66, v69
	v_mul_f32_e32 v74, v73, v68
	v_fma_f32 v75, -v64, v74, v73
	v_fmac_f32_e32 v74, v75, v68
	v_fma_f32 v64, -v64, v74, v73
	v_div_fmas_f32 v64, v64, v68, v74
	v_div_fixup_f32 v66, v64, v66, v69
	v_div_scale_f32 v64, s[4:5], v65, v65, v70
	v_rcp_f32_e32 v68, v64
	s_nop 0
	v_fma_f32 v69, -v64, v68, 1.0
	v_fmac_f32_e32 v68, v69, v68
	v_div_scale_f32 v69, vcc, v70, v65, v70
	v_mul_f32_e32 v73, v69, v68
	v_fma_f32 v74, -v64, v73, v69
	v_fmac_f32_e32 v73, v74, v68
	v_fma_f32 v64, -v64, v73, v69
	v_div_fmas_f32 v64, v64, v68, v73
	v_div_fixup_f32 v65, v64, v65, v70
	v_div_scale_f32 v64, s[4:5], v67, v67, v71
	v_rcp_f32_e32 v68, v64
	s_nop 0
	v_fma_f32 v69, -v64, v68, 1.0
	v_fmac_f32_e32 v68, v69, v68
	v_div_scale_f32 v69, vcc, v71, v67, v71
	v_mul_f32_e32 v70, v69, v68
	v_fma_f32 v73, -v64, v70, v69
	v_fmac_f32_e32 v70, v73, v68
	v_fma_f32 v64, -v64, v70, v69
	v_div_fmas_f32 v64, v64, v68, v70
	global_load_dwordx2 v[68:69], v[136:137], off
	v_div_fixup_f32 v64, v64, v67, v71
	s_waitcnt vmcnt(0)
	v_lshlrev_b32_e32 v67, 16, v68
	v_fmac_f32_e32 v67, v60, v72
	v_and_b32_e32 v60, 0xffff0000, v68
	v_fmac_f32_e32 v60, v61, v72
	v_lshlrev_b32_e32 v61, 16, v69
	v_fmac_f32_e32 v61, v62, v72
	v_and_b32_e32 v62, 0xffff0000, v69
	v_fmac_f32_e32 v62, v63, v72
	v_cvt_pk_bf16_f32 v60, v67, v60
	v_cvt_pk_bf16_f32 v61, v61, v62
	global_store_dwordx2 v[136:137], v[60:61], off
	s_waitcnt vmcnt(15)
	v_mov_b32_e32 v60, v222
	v_mov_b32_e32 v61, v223
	v_lshlrev_b32_e32 v62, 16, v60
	v_fmac_f32_e32 v62, v56, v72
	v_and_b32_e32 v56, 0xffff0000, v60
	v_fmac_f32_e32 v56, v57, v72
	v_lshlrev_b32_e32 v57, 16, v61
	v_fmac_f32_e32 v57, v58, v72
	v_and_b32_e32 v58, 0xffff0000, v61
	v_fmac_f32_e32 v58, v59, v72
	v_cvt_pk_bf16_f32 v56, v62, v56
	v_cvt_pk_bf16_f32 v57, v57, v58
	global_store_dwordx2 v[136:137], v[56:57], off offset:32
	s_waitcnt vmcnt(15)
	v_mov_b32_e32 v56, v224
	v_mov_b32_e32 v57, v225
	v_lshlrev_b32_e32 v58, 16, v56
	v_fmac_f32_e32 v58, v52, v72
	v_and_b32_e32 v52, 0xffff0000, v56
	v_fmac_f32_e32 v52, v53, v72
	v_lshlrev_b32_e32 v53, 16, v57
	v_fmac_f32_e32 v53, v54, v72
	v_and_b32_e32 v54, 0xffff0000, v57
	v_fmac_f32_e32 v54, v55, v72
	v_cvt_pk_bf16_f32 v52, v58, v52
	v_cvt_pk_bf16_f32 v53, v53, v54
	global_store_dwordx2 v[136:137], v[52:53], off offset:64
	s_waitcnt vmcnt(15)
	v_mov_b32_e32 v52, v226
	v_mov_b32_e32 v53, v227
	v_lshlrev_b32_e32 v54, 16, v52
	v_fmac_f32_e32 v54, v48, v72
	v_and_b32_e32 v48, 0xffff0000, v52
	v_fmac_f32_e32 v48, v49, v72
	v_lshlrev_b32_e32 v49, 16, v53
	v_fmac_f32_e32 v49, v50, v72
	v_and_b32_e32 v50, 0xffff0000, v53
	v_fmac_f32_e32 v50, v51, v72
	v_cvt_pk_bf16_f32 v48, v54, v48
	v_cvt_pk_bf16_f32 v49, v49, v50
	global_store_dwordx2 v[136:137], v[48:49], off offset:96
	s_waitcnt vmcnt(15)
	v_mov_b32_e32 v48, v228
	v_mov_b32_e32 v49, v229
	v_lshlrev_b32_e32 v50, 16, v48
	v_fmac_f32_e32 v50, v44, v66
	v_and_b32_e32 v44, 0xffff0000, v48
	v_fmac_f32_e32 v44, v45, v66
	v_lshlrev_b32_e32 v45, 16, v49
	v_fmac_f32_e32 v45, v46, v66
	v_and_b32_e32 v46, 0xffff0000, v49
	v_fmac_f32_e32 v46, v47, v66
	v_cvt_pk_bf16_f32 v44, v50, v44
	v_cvt_pk_bf16_f32 v45, v45, v46
	global_store_dwordx2 v[136:137], v[44:45], off offset:128
	s_waitcnt vmcnt(15)
	v_mov_b32_e32 v44, v230
	v_mov_b32_e32 v45, v231
	v_lshlrev_b32_e32 v46, 16, v44
	v_fmac_f32_e32 v46, v28, v66
	v_and_b32_e32 v28, 0xffff0000, v44
	v_fmac_f32_e32 v28, v29, v66
	v_lshlrev_b32_e32 v29, 16, v45
	v_fmac_f32_e32 v29, v30, v66
	v_and_b32_e32 v30, 0xffff0000, v45
	v_fmac_f32_e32 v30, v31, v66
	v_cvt_pk_bf16_f32 v28, v46, v28
	v_cvt_pk_bf16_f32 v29, v29, v30
	global_store_dwordx2 v[136:137], v[28:29], off offset:160
	s_waitcnt vmcnt(15)
	v_mov_b32_e32 v28, v232
	v_mov_b32_e32 v29, v233
	v_lshlrev_b32_e32 v30, 16, v28
	v_and_b32_e32 v28, 0xffff0000, v28
	v_lshlrev_b32_e32 v31, 16, v29
	v_and_b32_e32 v29, 0xffff0000, v29
	v_fmac_f32_e32 v28, v33, v66
	v_fmac_f32_e32 v29, v35, v66
	v_fmac_f32_e32 v30, v32, v66
	v_fmac_f32_e32 v31, v34, v66
	v_cvt_pk_bf16_f32 v28, v30, v28
	v_cvt_pk_bf16_f32 v29, v31, v29
	global_store_dwordx2 v[136:137], v[28:29], off offset:192
	s_waitcnt vmcnt(15)
	v_mov_b32_e32 v28, v234
	v_mov_b32_e32 v29, v235
	v_lshlrev_b32_e32 v30, 16, v28
	v_fmac_f32_e32 v30, v24, v66
	v_and_b32_e32 v24, 0xffff0000, v28
	v_fmac_f32_e32 v24, v25, v66
	v_lshlrev_b32_e32 v25, 16, v29
	v_fmac_f32_e32 v25, v26, v66
	v_and_b32_e32 v26, 0xffff0000, v29
	v_fmac_f32_e32 v26, v27, v66
	v_cvt_pk_bf16_f32 v24, v30, v24
	v_cvt_pk_bf16_f32 v25, v25, v26
	global_store_dwordx2 v[136:137], v[24:25], off offset:224
	s_waitcnt vmcnt(15)
	v_mov_b32_e32 v24, v236
	v_mov_b32_e32 v25, v237
	v_lshlrev_b32_e32 v26, 16, v24
	v_and_b32_e32 v24, 0xffff0000, v24
	v_lshlrev_b32_e32 v27, 16, v25
	v_and_b32_e32 v25, 0xffff0000, v25
	v_fmac_f32_e32 v24, v41, v65
	v_fmac_f32_e32 v25, v43, v65
	v_fmac_f32_e32 v26, v40, v65
	v_fmac_f32_e32 v27, v42, v65
	v_cvt_pk_bf16_f32 v24, v26, v24
	v_cvt_pk_bf16_f32 v25, v27, v25
	global_store_dwordx2 v[136:137], v[24:25], off offset:256
	s_waitcnt vmcnt(15)
	v_mov_b32_e32 v24, v238
	v_mov_b32_e32 v25, v239
	v_lshlrev_b32_e32 v26, 16, v24
	v_and_b32_e32 v24, 0xffff0000, v24
	v_lshlrev_b32_e32 v27, 16, v25
	v_and_b32_e32 v25, 0xffff0000, v25
	v_fmac_f32_e32 v24, v37, v65
	v_fmac_f32_e32 v25, v39, v65
	v_fmac_f32_e32 v26, v36, v65
	v_fmac_f32_e32 v27, v38, v65
	v_cvt_pk_bf16_f32 v24, v26, v24
	v_cvt_pk_bf16_f32 v25, v27, v25
	global_store_dwordx2 v[136:137], v[24:25], off offset:288
	s_waitcnt vmcnt(15)
	v_mov_b32_e32 v24, v240
	v_mov_b32_e32 v25, v241
	v_lshlrev_b32_e32 v26, 16, v24
	v_fmac_f32_e32 v26, v20, v65
	v_and_b32_e32 v20, 0xffff0000, v24
	v_fmac_f32_e32 v20, v21, v65
	v_lshlrev_b32_e32 v21, 16, v25
	v_fmac_f32_e32 v21, v22, v65
	v_and_b32_e32 v22, 0xffff0000, v25
	v_fmac_f32_e32 v22, v23, v65
	v_cvt_pk_bf16_f32 v20, v26, v20
	v_cvt_pk_bf16_f32 v21, v21, v22
	global_store_dwordx2 v[136:137], v[20:21], off offset:320
	s_waitcnt vmcnt(15)
	v_mov_b32_e32 v20, v242
	v_mov_b32_e32 v21, v243
	v_lshlrev_b32_e32 v22, 16, v20
	v_fmac_f32_e32 v22, v16, v65
	v_and_b32_e32 v16, 0xffff0000, v20
	v_fmac_f32_e32 v16, v17, v65
	v_lshlrev_b32_e32 v17, 16, v21
	v_fmac_f32_e32 v17, v18, v65
	v_and_b32_e32 v18, 0xffff0000, v21
	v_fmac_f32_e32 v18, v19, v65
	v_cvt_pk_bf16_f32 v16, v22, v16
	v_cvt_pk_bf16_f32 v17, v17, v18
	global_store_dwordx2 v[136:137], v[16:17], off offset:352
	s_waitcnt vmcnt(15)
	v_mov_b32_e32 v16, v244
	v_mov_b32_e32 v17, v245
	v_lshlrev_b32_e32 v18, 16, v16
	v_fmac_f32_e32 v18, v12, v64
	v_and_b32_e32 v12, 0xffff0000, v16
	v_fmac_f32_e32 v12, v13, v64
	v_lshlrev_b32_e32 v13, 16, v17
	v_fmac_f32_e32 v13, v14, v64
	v_and_b32_e32 v14, 0xffff0000, v17
	v_fmac_f32_e32 v14, v15, v64
	v_cvt_pk_bf16_f32 v12, v18, v12
	v_cvt_pk_bf16_f32 v13, v13, v14
	global_store_dwordx2 v[136:137], v[12:13], off offset:384
	s_waitcnt vmcnt(15)
	v_mov_b32_e32 v12, v246
	v_mov_b32_e32 v13, v247
	v_lshlrev_b32_e32 v14, 16, v12
	v_fmac_f32_e32 v14, v8, v64
	v_and_b32_e32 v8, 0xffff0000, v12
	v_fmac_f32_e32 v8, v9, v64
	v_lshlrev_b32_e32 v9, 16, v13
	v_fmac_f32_e32 v9, v10, v64
	v_and_b32_e32 v10, 0xffff0000, v13
	v_fmac_f32_e32 v10, v11, v64
	v_cvt_pk_bf16_f32 v8, v14, v8
	v_cvt_pk_bf16_f32 v9, v9, v10
	global_store_dwordx2 v[136:137], v[8:9], off offset:416
	s_waitcnt vmcnt(15)
	v_mov_b32_e32 v8, v248
	v_mov_b32_e32 v9, v249
	v_lshlrev_b32_e32 v10, 16, v8
	v_fmac_f32_e32 v10, v4, v64
	v_and_b32_e32 v4, 0xffff0000, v8
	v_fmac_f32_e32 v4, v5, v64
	v_lshlrev_b32_e32 v5, 16, v9
	v_fmac_f32_e32 v5, v6, v64
	v_and_b32_e32 v6, 0xffff0000, v9
	v_fmac_f32_e32 v6, v7, v64
	v_cvt_pk_bf16_f32 v4, v10, v4
	v_cvt_pk_bf16_f32 v5, v5, v6
	global_store_dwordx2 v[136:137], v[4:5], off offset:448
	s_waitcnt vmcnt(15)
	v_mov_b32_e32 v4, v250
	v_mov_b32_e32 v5, v251
	v_lshlrev_b32_e32 v6, 16, v4
	v_fmac_f32_e32 v6, v0, v64
	v_and_b32_e32 v0, 0xffff0000, v4
	v_fmac_f32_e32 v0, v1, v64
	v_lshlrev_b32_e32 v1, 16, v5
	v_fmac_f32_e32 v1, v2, v64
	v_and_b32_e32 v2, 0xffff0000, v5
	v_cvt_pk_bf16_f32 v0, v6, v0
	v_fmac_f32_e32 v2, v3, v64
	v_cvt_pk_bf16_f32 v1, v1, v2
	global_store_dwordx2 v[136:137], v[0:1], off offset:480
	v_sub_u32_e64 v0, v214, 8 clamp
	s_nop 0
	v_readfirstlane_b32 s4, v0
	s_lshl_b64 s[4:5], -1, s4
	v_and_b32_e32 v1, s5, v220
	v_and_b32_e32 v0, s4, v221
	v_cmp_eq_u64_e32 vcc, 0, v[0:1]
	s_cbranch_vccnz .LBB0_117
	v_ffbl_b32_e32 v5, v1
	s_mov_b64 s[4:5], 0x1800000
	v_mov_b32_e32 v171, v153
	v_ffbl_b32_e32 v4, v0
	v_add_u32_e64 v5, v5, 32 clamp
	v_lshl_add_u64 v[168:169], v[168:169], 0, s[4:5]
	v_lshl_add_u64 v[2:3], v[166:167], 0, v[170:171]
	s_mov_b64 s[4:5], 0x1000
	v_min_u32_e32 v50, v5, v4
	v_lshl_add_u64 v[4:5], v[0:1], 0, -1
	v_lshl_add_u64 v[2:3], v[2:3], 0, s[4:5]
	v_and_b32_e32 v48, v4, v0
	v_and_b32_e32 v49, v5, v1
	v_mul_lo_u32 v0, v50, s72
	v_mov_b32_e32 v1, v153
	s_movk_i32 s6, 0xc00
	v_lshl_add_u64 v[0:1], v[2:3], 0, v[0:1]
	v_mov_b32_e32 v161, v153
	v_mad_i64_i32 v[158:159], s[4:5], v158, s6, 0
	v_lshlrev_b32_e32 v4, 7, v50
	v_mov_b32_e32 v5, v153
	v_lshl_add_u64 v[0:1], v[0:1], 0, v[160:161]
	v_readfirstlane_b32 s4, v146
	v_lshl_add_u64 v[4:5], v[168:169], 0, v[4:5]
	v_lshl_add_u64 v[6:7], v[158:159], 1, v[0:1]
	s_mov_b32 m0, s4
	v_readfirstlane_b32 s4, v216
	v_lshl_add_u64 v[8:9], v[4:5], 0, v[164:165]
	global_load_lds_dwordx4 v[6:7], off
	s_mov_b32 m0, s4
	v_mad_i64_i32 v[156:157], s[4:5], v156, s6, 0
	v_lshl_add_u64 v[8:9], v[8:9], 0, v[152:153]
	v_readfirstlane_b32 s4, v148
	global_load_lds_dwordx4 v[8:9], off
	v_lshl_add_u64 v[0:1], v[156:157], 1, v[0:1]
	v_lshl_add_u64 v[4:5], v[4:5], 0, v[162:163]
	v_mov_b32_e32 v151, v153
	s_mov_b32 m0, s4
	v_readfirstlane_b32 s4, v215
	v_lshl_add_u64 v[4:5], v[4:5], 0, v[150:151]
	global_load_lds_dwordx4 v[0:1], off
	s_mov_b32 m0, s4
	v_cmp_lt_i32_e32 vcc, v218, v219
	global_load_lds_dwordx4 v[4:5], off
	s_nop 0
	v_cndmask_b32_e32 v0, v200, v218, vcc
	v_cmp_lt_i32_e32 vcc, v217, v219
	v_lshlrev_b32_e32 v183, 2, v0
	v_lshl_add_u64 v[160:161], v[2:3], 0, v[160:161]
	v_cndmask_b32_e32 v0, v200, v217, vcc
	v_lshlrev_b32_e32 v186, 2, v0
	v_mov_b32_e32 v0, 0
	s_mov_b32 s84, 0
	v_mov_b32_e32 v188, 0xf149f2ca
	v_mov_b32_e32 v170, 0xf149f2ca
	v_mov_b32_e32 v182, 0xf149f2ca
	v_mov_b32_e32 v184, 0xf149f2ca
	v_mov_b32_e32 v1, v0
	v_mov_b32_e32 v2, v0
	v_mov_b32_e32 v3, v0
	v_mov_b32_e32 v16, v0
	v_mov_b32_e32 v17, v0
	v_mov_b32_e32 v18, v0
	v_mov_b32_e32 v19, v0
	v_mov_b32_e32 v24, v0
	v_mov_b32_e32 v25, v0
	v_mov_b32_e32 v26, v0
	v_mov_b32_e32 v27, v0
	v_mov_b32_e32 v88, v0
	v_mov_b32_e32 v89, v0
	v_mov_b32_e32 v90, v0
	v_mov_b32_e32 v91, v0
	v_mov_b32_e32 v4, v0
	v_mov_b32_e32 v5, v0
	v_mov_b32_e32 v6, v0
	v_mov_b32_e32 v7, v0
	v_mov_b32_e32 v20, v0
	v_mov_b32_e32 v21, v0
	v_mov_b32_e32 v22, v0
	v_mov_b32_e32 v23, v0
	v_mov_b32_e32 v28, v0
	v_mov_b32_e32 v29, v0
	v_mov_b32_e32 v30, v0
	v_mov_b32_e32 v31, v0
	v_mov_b32_e32 v92, v0
	v_mov_b32_e32 v93, v0
	v_mov_b32_e32 v94, v0
	v_mov_b32_e32 v95, v0
	v_mov_b32_e32 v8, v0
	v_mov_b32_e32 v9, v0
	v_mov_b32_e32 v10, v0
	v_mov_b32_e32 v11, v0
	v_mov_b32_e32 v40, v0
	v_mov_b32_e32 v41, v0
	v_mov_b32_e32 v42, v0
	v_mov_b32_e32 v43, v0
	v_mov_b32_e32 v32, v0
	v_mov_b32_e32 v33, v0
	v_mov_b32_e32 v34, v0
	v_mov_b32_e32 v35, v0
	v_mov_b32_e32 v96, v0
	v_mov_b32_e32 v97, v0
	v_mov_b32_e32 v98, v0
	v_mov_b32_e32 v99, v0
	v_mov_b32_e32 v12, v0
	v_mov_b32_e32 v13, v0
	v_mov_b32_e32 v14, v0
	v_mov_b32_e32 v15, v0
	v_mov_b32_e32 v44, v0
	v_mov_b32_e32 v45, v0
	v_mov_b32_e32 v46, v0
	v_mov_b32_e32 v47, v0
	v_mov_b32_e32 v36, v0
	v_mov_b32_e32 v37, v0
	v_mov_b32_e32 v38, v0
	v_mov_b32_e32 v39, v0
	v_mov_b32_e32 v100, v0
	v_mov_b32_e32 v101, v0
	v_mov_b32_e32 v102, v0
	v_mov_b32_e32 v103, v0
	v_mov_b32_e32 v164, v0
	v_mov_b32_e32 v165, v0
	v_mov_b32_e32 v132, v0
	v_mov_b32_e32 v133, v0
	s_waitcnt vmcnt(0) lgkmcnt(0)
	s_barrier

.LBB0_718:
	s_mov_b64 s[4:5], exec
	s_load_dword s13, s[88:89], 0x0
	v_lshrrev_b32_e32 v0, 6, v198
	v_lshlrev_b32_e32 v58, 4, v200
	v_readfirstlane_b32 s12, v0
	v_lshlrev_b32_e32 v59, 3, v200
	v_readlane_b32 s8, v253, 63
	s_nop 0
	s_add_u32 s12, s12, s8
	s_cmp_lt_u32 s12, 0x8000
	s_cbranch_scc0 .LBB0_721
	v_xor_b32_e32 v52, 32, v200
	v_lshlrev_b32_e32 v52, 2, v52
	v_xor_b32_e32 v53, 16, v200
	v_lshlrev_b32_e32 v53, 2, v53
	v_xor_b32_e32 v54, 8, v200
	v_lshlrev_b32_e32 v54, 2, v54
	v_xor_b32_e32 v55, 4, v200
	v_lshlrev_b32_e32 v55, 2, v55
	v_xor_b32_e32 v56, 2, v200
	v_lshlrev_b32_e32 v56, 2, v56
	v_xor_b32_e32 v57, 1, v200
	v_lshlrev_b32_e32 v57, 2, v57
	global_load_dwordx4 v[2:5], v58, s[46:47]
	global_load_dwordx4 v[6:9], v58, s[46:47] offset:1024
	global_load_dwordx4 v[10:13], v58, s[46:47] offset:2048
	global_load_dwordx4 v[14:17], v58, s[46:47] offset:3072
	s_lshl_b32 s16, s12, 12
	s_lshr_b32 s17, s12, 20
	s_add_u32 s8, s44, s16
	s_addc_u32 s9, s45, s17
	s_lshl_b32 s16, s12, 11
	s_add_u32 s10, s96, s16
	s_addc_u32 s11, s97, 0
	s_waitcnt lgkmcnt(0)
	s_lshl_b32 s13, s13, 2
	s_lshl_b32 s18, s13, 12
	s_lshl_b32 s19, s13, 11
	global_load_dwordx4 v[20:23], v58, s[8:9]
	global_load_dwordx4 v[24:27], v58, s[8:9] offset:1024
	global_load_dwordx4 v[28:31], v58, s[8:9] offset:2048
	global_load_dwordx4 v[32:35], v58, s[8:9] offset:3072
.Lnorm_a:
	s_add_u32 s20, s12, s13
	s_add_u32 s8, s8, s18
	s_addc_u32 s9, s9, 0
	s_cmp_lt_u32 s20, 0x8000
	s_cbranch_scc0 .Lnorm_a_last
	global_load_dwordx4 v[36:39], v58, s[8:9]
	global_load_dwordx4 v[40:43], v58, s[8:9] offset:1024
	global_load_dwordx4 v[44:47], v58, s[8:9] offset:2048
	global_load_dwordx4 v[48:51], v58, s[8:9] offset:3072
	s_waitcnt vmcnt(4)
	s_branch .Lnorm_a_go

.Lnorm_a_go:
	v_mul_f32_e32 v60, v21, v21
	v_fmac_f32_e32 v60, v20, v20
	v_fmac_f32_e32 v60, v22, v22
	v_fmac_f32_e32 v60, v23, v23
	v_mul_f32_e32 v61, v25, v25
	v_fmac_f32_e32 v61, v24, v24
	v_fmac_f32_e32 v61, v26, v26
	v_fmac_f32_e32 v61, v27, v27
	v_mul_f32_e32 v62, v29, v29
	v_fmac_f32_e32 v62, v28, v28
	v_fmac_f32_e32 v62, v30, v30
	v_fmac_f32_e32 v62, v31, v31
	v_mul_f32_e32 v63, v33, v33
	v_fmac_f32_e32 v63, v32, v32
	v_fmac_f32_e32 v63, v34, v34
	v_fmac_f32_e32 v63, v35, v35
	v_add_f32_e32 v64, v60, v61
	v_add_f32_e32 v64, v64, v62
	v_add_f32_e32 v64, v64, v63
	ds_bpermute_b32 v65, v52, v64
	s_waitcnt lgkmcnt(0)
	v_add_f32_e32 v64, v64, v65
	ds_bpermute_b32 v65, v53, v64
	s_waitcnt lgkmcnt(0)
	v_add_f32_e32 v64, v64, v65
	ds_bpermute_b32 v65, v54, v64
	s_waitcnt lgkmcnt(0)
	v_add_f32_e32 v64, v64, v65
	ds_bpermute_b32 v65, v55, v64
	s_waitcnt lgkmcnt(0)
	v_add_f32_e32 v64, v64, v65
	ds_bpermute_b32 v65, v56, v64
	s_waitcnt lgkmcnt(0)
	v_add_f32_e32 v64, v64, v65
	ds_bpermute_b32 v65, v57, v64
	s_waitcnt lgkmcnt(0)
	v_add_f32_e32 v64, v64, v65
	v_fmamk_f32 v64, v64, 0x3a800000, v199
	v_cmp_gt_f32_e32 vcc, s73, v64
	v_mul_f32_e32 v65, 0x4b800000, v64
	s_nop 0
	v_cndmask_b32_e32 v64, v64, v65, vcc
	v_rsq_f32_e32 v64, v64
	s_nop 0
	v_mul_f32_e32 v65, 0x45800000, v64
	v_cndmask_b32_e32 v66, v64, v65, vcc
	v_mul_f32_e32 v60, v20, v66
	v_mul_f32_e32 v61, v21, v66
	v_mul_f32_e32 v62, v22, v66
	v_mul_f32_e32 v63, v23, v66
	v_mul_f32_e32 v60, v2, v60
	v_mul_f32_e32 v61, v3, v61
	v_mul_f32_e32 v62, v4, v62
	v_mul_f32_e32 v63, v5, v63
	v_cvt_pk_bf16_f32 v68, v60, v61
	v_cvt_pk_bf16_f32 v69, v62, v63
	global_store_dwordx2 v59, v[68:69], s[10:11]
	v_mul_f32_e32 v60, v24, v66
	v_mul_f32_e32 v61, v25, v66
	v_mul_f32_e32 v62, v26, v66
	v_mul_f32_e32 v63, v27, v66
	v_mul_f32_e32 v60, v6, v60
	v_mul_f32_e32 v61, v7, v61
	v_mul_f32_e32 v62, v8, v62
	v_mul_f32_e32 v63, v9, v63
	v_cvt_pk_bf16_f32 v70, v60, v61
	v_cvt_pk_bf16_f32 v71, v62, v63
	global_store_dwordx2 v59, v[70:71], s[10:11] offset:512
	v_mul_f32_e32 v60, v28, v66
	v_mul_f32_e32 v61, v29, v66
	v_mul_f32_e32 v62, v30, v66
	v_mul_f32_e32 v63, v31, v66
	v_mul_f32_e32 v60, v10, v60
	v_mul_f32_e32 v61, v11, v61
	v_mul_f32_e32 v62, v12, v62
	v_mul_f32_e32 v63, v13, v63
	v_cvt_pk_bf16_f32 v72, v60, v61
	v_cvt_pk_bf16_f32 v73, v62, v63
	global_store_dwordx2 v59, v[72:73], s[10:11] offset:1024
	v_mul_f32_e32 v60, v32, v66
	v_mul_f32_e32 v61, v33, v66
	v_mul_f32_e32 v62, v34, v66
	v_mul_f32_e32 v63, v35, v66
	v_mul_f32_e32 v60, v14, v60
	v_mul_f32_e32 v61, v15, v61
	v_mul_f32_e32 v62, v16, v62
	v_mul_f32_e32 v63, v17, v63
	v_cvt_pk_bf16_f32 v74, v60, v61
	v_cvt_pk_bf16_f32 v75, v62, v63
	global_store_dwordx2 v59, v[74:75], s[10:11] offset:1536
	s_add_u32 s10, s10, s19
	s_addc_u32 s11, s11, 0
	s_mov_b32 s12, s20
	s_cmp_lt_u32 s12, 0x8000
	s_cbranch_scc0 .LBB0_721
.Lnorm_b:
	s_add_u32 s20, s12, s13
	s_add_u32 s8, s8, s18
	s_addc_u32 s9, s9, 0
	s_cmp_lt_u32 s20, 0x8000
	s_cbranch_scc0 .Lnorm_b_last
	global_load_dwordx4 v[20:23], v58, s[8:9]
	global_load_dwordx4 v[24:27], v58, s[8:9] offset:1024
	global_load_dwordx4 v[28:31], v58, s[8:9] offset:2048
	global_load_dwordx4 v[32:35], v58, s[8:9] offset:3072
	s_waitcnt vmcnt(4)
	s_branch .Lnorm_b_go

.Lnorm_b_go:
	v_mul_f32_e32 v60, v37, v37
	v_fmac_f32_e32 v60, v36, v36
	v_fmac_f32_e32 v60, v38, v38
	v_fmac_f32_e32 v60, v39, v39
	v_mul_f32_e32 v61, v41, v41
	v_fmac_f32_e32 v61, v40, v40
	v_fmac_f32_e32 v61, v42, v42
	v_fmac_f32_e32 v61, v43, v43
	v_mul_f32_e32 v62, v45, v45
	v_fmac_f32_e32 v62, v44, v44
	v_fmac_f32_e32 v62, v46, v46
	v_fmac_f32_e32 v62, v47, v47
	v_mul_f32_e32 v63, v49, v49
	v_fmac_f32_e32 v63, v48, v48
	v_fmac_f32_e32 v63, v50, v50
	v_fmac_f32_e32 v63, v51, v51
	v_add_f32_e32 v64, v60, v61
	v_add_f32_e32 v64, v64, v62
	v_add_f32_e32 v64, v64, v63
	ds_bpermute_b32 v65, v52, v64
	s_waitcnt lgkmcnt(0)
	v_add_f32_e32 v64, v64, v65
	ds_bpermute_b32 v65, v53, v64
	s_waitcnt lgkmcnt(0)
	v_add_f32_e32 v64, v64, v65
	ds_bpermute_b32 v65, v54, v64
	s_waitcnt lgkmcnt(0)
	v_add_f32_e32 v64, v64, v65
	ds_bpermute_b32 v65, v55, v64
	s_waitcnt lgkmcnt(0)
	v_add_f32_e32 v64, v64, v65
	ds_bpermute_b32 v65, v56, v64
	s_waitcnt lgkmcnt(0)
	v_add_f32_e32 v64, v64, v65
	ds_bpermute_b32 v65, v57, v64
	s_waitcnt lgkmcnt(0)
	v_add_f32_e32 v64, v64, v65
	v_fmamk_f32 v64, v64, 0x3a800000, v199
	v_cmp_gt_f32_e32 vcc, s73, v64
	v_mul_f32_e32 v65, 0x4b800000, v64
	s_nop 0
	v_cndmask_b32_e32 v64, v64, v65, vcc
	v_rsq_f32_e32 v64, v64
	s_nop 0
	v_mul_f32_e32 v65, 0x45800000, v64
	v_cndmask_b32_e32 v66, v64, v65, vcc
	v_mul_f32_e32 v60, v36, v66
	v_mul_f32_e32 v61, v37, v66
	v_mul_f32_e32 v62, v38, v66
	v_mul_f32_e32 v63, v39, v66
	v_mul_f32_e32 v60, v2, v60
	v_mul_f32_e32 v61, v3, v61
	v_mul_f32_e32 v62, v4, v62
	v_mul_f32_e32 v63, v5, v63
	v_cvt_pk_bf16_f32 v68, v60, v61
	v_cvt_pk_bf16_f32 v69, v62, v63
	global_store_dwordx2 v59, v[68:69], s[10:11]
	v_mul_f32_e32 v60, v40, v66
	v_mul_f32_e32 v61, v41, v66
	v_mul_f32_e32 v62, v42, v66
	v_mul_f32_e32 v63, v43, v66
	v_mul_f32_e32 v60, v6, v60
	v_mul_f32_e32 v61, v7, v61
	v_mul_f32_e32 v62, v8, v62
	v_mul_f32_e32 v63, v9, v63
	v_cvt_pk_bf16_f32 v70, v60, v61
	v_cvt_pk_bf16_f32 v71, v62, v63
	global_store_dwordx2 v59, v[70:71], s[10:11] offset:512
	v_mul_f32_e32 v60, v44, v66
	v_mul_f32_e32 v61, v45, v66
	v_mul_f32_e32 v62, v46, v66
	v_mul_f32_e32 v63, v47, v66
	v_mul_f32_e32 v60, v10, v60
	v_mul_f32_e32 v61, v11, v61
	v_mul_f32_e32 v62, v12, v62
	v_mul_f32_e32 v63, v13, v63
	v_cvt_pk_bf16_f32 v72, v60, v61
	v_cvt_pk_bf16_f32 v73, v62, v63
	global_store_dwordx2 v59, v[72:73], s[10:11] offset:1024
	v_mul_f32_e32 v60, v48, v66
	v_mul_f32_e32 v61, v49, v66
	v_mul_f32_e32 v62, v50, v66
	v_mul_f32_e32 v63, v51, v66
	v_mul_f32_e32 v60, v14, v60
	v_mul_f32_e32 v61, v15, v61
	v_mul_f32_e32 v62, v16, v62
	v_mul_f32_e32 v63, v17, v63
	v_cvt_pk_bf16_f32 v74, v60, v61
	v_cvt_pk_bf16_f32 v75, v62, v63
	global_store_dwordx2 v59, v[74:75], s[10:11] offset:1536
	s_add_u32 s10, s10, s19
	s_addc_u32 s11, s11, 0
	s_mov_b32 s12, s20
	s_cmp_lt_u32 s12, 0x8000
	s_cbranch_scc0 .LBB0_721
	s_branch .Lnorm_a
